# stack of the individually neutral exact edits on the write-through version: P1 log-forget trim, P7 relu canonicalisation trim, P0 two-item pipelining, late-tile workgroups not waiting at P2|P3
# speedup vs baseline: 1.0009x; 1.0009x over previous
; __device__ __forceinline__ u32x4 pack8(const f32x4 a, const f32x4 b) { u32x4 w; w.x = cvt_pk_bf16(a[0], a[1]); w.y = cvt_pk_bf16(a[2], a[3]); w.z = cvt_pk_bf16(b[0], b[1]); w.w = cvt_pk_bf16(b[2], b[3]); return w; }
;     __device__ __forceinline__ void operator()(const f32x4 (&acc)[2][2][4][2], const Unit& u, int wr, int wc, int fr, int fq) const {
;     ...
;         for (int ai = 0; ai < 2; ++ai)
; #pragma unroll
;             for (int m = 0; m < 4; ++m) {
; #pragma unroll
;                 for (int bj = 0; bj < 2; ++bj) { f32x4 v0 = acc[ai][bj][m][0], v1 = acc[ai][bj][m][1];
; #pragma unroll
;                     for (int i = 0; i < 4; ++i) { const float a = fmaxf(v0[i], 0.f), b = fmaxf(v1[i], 0.f); v0[i] = a * a; v1[i] = b * b; }
;                     *(u32x4*)(hb + ((size_t)(u.pm * 64 + u.pn * 4 + bj * 2 + (wc >> 1)) * 256 + rl0 + ai * HALF + m * 16) * 64 + cin) = pack8(v0, v1); } }
.LBB0_1247:
	s_lshl_b32 s17, s28, 6
	s_lshl_b32 s19, s29, 2
	s_add_i32 s17, s17, s19
	s_or_b32 s30, s17, s47
	s_ashr_i32 s31, s30, 31
	s_lshl_b64 s[28:29], s[30:31], 15
	s_add_u32 s28, s26, s28
	s_addc_u32 s29, s27, s29
	s_or_b32 s30, s30, 2
	v_max_f32_e32 v126, 0, v126
	v_max_f32_e32 v122, 0, v122
	v_max_f32_e32 v127, 0, v127
	v_max_f32_e32 v123, 0, v123
	s_ashr_i32 s31, s30, 31
	v_pk_mul_f32 v[126:127], v[126:127], v[126:127]
	v_pk_mul_f32 v[122:123], v[122:123], v[122:123]
	v_max_f32_e32 v128, 0, v128
	v_max_f32_e32 v124, 0, v124
	v_max_f32_e32 v129, 0, v129
	v_max_f32_e32 v125, 0, v125
	s_lshl_b64 s[30:31], s[30:31], 15
	v_pk_mul_f32 v[128:129], v[128:129], v[128:129]
	v_pk_mul_f32 v[158:159], v[124:125], v[124:125]
	v_cvt_pk_bf16_f32 v124, v126, v127
	v_cvt_pk_bf16_f32 v126, v122, v123
	v_lshl_add_u64 v[122:123], s[28:29], 0, v[140:141]
	v_max_f32_e32 v118, 0, v118
	v_max_f32_e32 v114, 0, v114
	v_max_f32_e32 v119, 0, v119
	v_max_f32_e32 v115, 0, v115
	s_add_u32 s30, s26, s30
	v_cvt_pk_bf16_f32 v125, v128, v129
	v_cvt_pk_bf16_f32 v127, v158, v159
	v_lshl_add_u64 v[122:123], v[122:123], 0, v[138:139]
	v_pk_mul_f32 v[118:119], v[118:119], v[118:119]
	v_pk_mul_f32 v[114:115], v[114:115], v[114:115]
	v_max_f32_e32 v120, 0, v120
	v_max_f32_e32 v116, 0, v116
	v_max_f32_e32 v121, 0, v121
	v_max_f32_e32 v117, 0, v117
	s_addc_u32 s31, s27, s31
	global_store_dwordx4 v[122:123], v[124:127], off
	s_nop 0
	v_pk_mul_f32 v[120:121], v[120:121], v[120:121]
	v_pk_mul_f32 v[124:125], v[116:117], v[116:117]
	v_cvt_pk_bf16_f32 v116, v118, v119
	v_cvt_pk_bf16_f32 v118, v114, v115
	v_lshl_add_u64 v[114:115], s[30:31], 0, v[140:141]
	v_cvt_pk_bf16_f32 v117, v120, v121
	v_cvt_pk_bf16_f32 v119, v124, v125
	v_lshl_add_u64 v[114:115], v[114:115], 0, v[138:139]
	v_max_f32_e32 v106, 0, v106
	v_max_f32_e32 v107, 0, v107
	global_store_dwordx4 v[114:115], v[116:119], off
	s_nop 1
	v_pk_mul_f32 v[116:117], v[106:107], v[106:107]
	v_max_f32_e32 v107, v108, v108
	v_max_f32_e32 v106, v112, v112
	v_max_f32_e32 v108, 0, v107
	v_max_f32_e32 v107, v113, v113
	v_max_f32_e32 v110, 0, v110
	v_max_f32_e32 v111, 0, v111
	v_max_f32_e32 v106, 0, v106
	v_max_f32_e32 v107, 0, v107
	v_max_f32_e32 v109, 0, v109
	v_pk_mul_f32 v[110:111], v[110:111], v[110:111]
	v_pk_mul_f32 v[112:113], v[106:107], v[106:107]
	v_pk_mul_f32 v[118:119], v[108:109], v[108:109]
	v_cvt_pk_bf16_f32 v106, v110, v111
	v_cvt_pk_bf16_f32 v107, v112, v113
	v_cvt_pk_bf16_f32 v108, v116, v117
	v_cvt_pk_bf16_f32 v109, v118, v119
	v_max_f32_e32 v98, 0, v98
	v_max_f32_e32 v99, 0, v99
	global_store_dwordx4 v[122:123], v[106:109], off offset:2048
	s_nop 1
	v_pk_mul_f32 v[106:107], v[98:99], v[98:99]
	v_max_f32_e32 v99, v100, v100
	v_max_f32_e32 v98, v104, v104
	v_max_f32_e32 v100, 0, v99
	v_max_f32_e32 v99, v105, v105
	v_max_f32_e32 v102, 0, v102
	v_max_f32_e32 v103, 0, v103
	v_max_f32_e32 v98, 0, v98
	v_max_f32_e32 v99, 0, v99
	v_max_f32_e32 v101, 0, v101
	v_pk_mul_f32 v[102:103], v[102:103], v[102:103]
	v_pk_mul_f32 v[104:105], v[98:99], v[98:99]
	v_pk_mul_f32 v[108:109], v[100:101], v[100:101]
	v_cvt_pk_bf16_f32 v98, v102, v103
	v_cvt_pk_bf16_f32 v99, v104, v105
	v_cvt_pk_bf16_f32 v100, v106, v107
	v_cvt_pk_bf16_f32 v101, v108, v109
	v_max_f32_e32 v90, 0, v90
	v_max_f32_e32 v91, 0, v91
	global_store_dwordx4 v[114:115], v[98:101], off offset:2048
	s_nop 1
	v_pk_mul_f32 v[98:99], v[90:91], v[90:91]
	v_max_f32_e32 v91, v92, v92
	v_max_f32_e32 v94, 0, v94
	v_max_f32_e32 v95, 0, v95
	v_max_f32_e32 v90, v96, v96
	v_max_f32_e32 v92, 0, v91
	v_max_f32_e32 v91, v97, v97
	v_pk_mul_f32 v[94:95], v[94:95], v[94:95]
	v_max_f32_e32 v90, 0, v90
	v_max_f32_e32 v91, 0, v91
	v_max_f32_e32 v93, 0, v93
	v_pk_mul_f32 v[96:97], v[90:91], v[90:91]
	v_pk_mul_f32 v[100:101], v[92:93], v[92:93]
	v_cvt_pk_bf16_f32 v90, v94, v95
	v_lshl_add_u64 v[94:95], s[28:29], 0, v[142:143]
	v_cvt_pk_bf16_f32 v91, v96, v97
	v_cvt_pk_bf16_f32 v92, v98, v99
	v_cvt_pk_bf16_f32 v93, v100, v101
	v_lshl_add_u64 v[94:95], v[94:95], 0, v[138:139]
	v_max_f32_e32 v82, 0, v82
	v_max_f32_e32 v83, 0, v83
	global_store_dwordx4 v[94:95], v[90:93], off
	s_nop 1
	v_pk_mul_f32 v[90:91], v[82:83], v[82:83]
	v_max_f32_e32 v83, v84, v84
	v_max_f32_e32 v86, 0, v86
	v_max_f32_e32 v87, 0, v87
	v_max_f32_e32 v82, v88, v88
	v_max_f32_e32 v84, 0, v83
	v_max_f32_e32 v83, v89, v89
	v_pk_mul_f32 v[86:87], v[86:87], v[86:87]
	v_max_f32_e32 v82, 0, v82
	v_max_f32_e32 v83, 0, v83
	v_max_f32_e32 v85, 0, v85
	v_pk_mul_f32 v[88:89], v[82:83], v[82:83]
	v_pk_mul_f32 v[92:93], v[84:85], v[84:85]
	v_cvt_pk_bf16_f32 v82, v86, v87
	v_lshl_add_u64 v[86:87], s[30:31], 0, v[142:143]
	v_cvt_pk_bf16_f32 v83, v88, v89
	v_cvt_pk_bf16_f32 v84, v90, v91
	v_cvt_pk_bf16_f32 v85, v92, v93
	v_lshl_add_u64 v[86:87], v[86:87], 0, v[138:139]
	v_max_f32_e32 v74, 0, v74
	v_max_f32_e32 v75, 0, v75
	global_store_dwordx4 v[86:87], v[82:85], off
	s_nop 1
	v_pk_mul_f32 v[82:83], v[74:75], v[74:75]
	v_max_f32_e32 v75, v76, v76
	v_max_f32_e32 v78, 0, v78
	v_max_f32_e32 v79, 0, v79
	v_max_f32_e32 v74, v80, v80
	v_max_f32_e32 v76, 0, v75
	v_max_f32_e32 v75, v81, v81
	v_pk_mul_f32 v[78:79], v[78:79], v[78:79]
	v_max_f32_e32 v74, 0, v74
	v_max_f32_e32 v75, 0, v75
	v_max_f32_e32 v77, 0, v77
	v_pk_mul_f32 v[80:81], v[74:75], v[74:75]
	v_pk_mul_f32 v[84:85], v[76:77], v[76:77]
	v_cvt_pk_bf16_f32 v74, v78, v79
	v_lshl_add_u64 v[78:79], s[28:29], 0, v[144:145]
	v_cvt_pk_bf16_f32 v75, v80, v81
	v_cvt_pk_bf16_f32 v76, v82, v83
	v_cvt_pk_bf16_f32 v77, v84, v85
	v_lshl_add_u64 v[78:79], v[78:79], 0, v[138:139]
	v_max_f32_e32 v66, 0, v66
	v_max_f32_e32 v67, 0, v67
	global_store_dwordx4 v[78:79], v[74:77], off
	s_nop 1
; __device__ __forceinline__ u32x4 pack8(const f32x4 a, const f32x4 b) { u32x4 w; w.x = cvt_pk_bf16(a[0], a[1]); w.y = cvt_pk_bf16(a[2], a[3]); w.z = cvt_pk_bf16(b[0], b[1]); w.w = cvt_pk_bf16(b[2], b[3]); return w; }
; #define PG8_BAR __builtin_amdgcn_s_barrier()
;     __device__ __forceinline__ void operator()(const f32x4 (&acc)[2][2][4][2], const Unit& u, int wr, int wc, int fr, int fq) const {
;     ...
;         for (int ai = 0; ai < 2; ++ai)
; #pragma unroll
;             for (int m = 0; m < 4; ++m) {
; #pragma unroll
;                 for (int bj = 0; bj < 2; ++bj) { f32x4 v0 = acc[ai][bj][m][0], v1 = acc[ai][bj][m][1];
; #pragma unroll
;                     for (int i = 0; i < 4; ++i) { const float a = fmaxf(v0[i], 0.f), b = fmaxf(v1[i], 0.f); v0[i] = a * a; v1[i] = b * b; }
;                     *(u32x4*)(hb + ((size_t)(u.pm * 64 + u.pn * 4 + bj * 2 + (wc >> 1)) * 256 + rl0 + ai * HALF + m * 16) * 64 + cin) = pack8(v0, v1); } }
; template <class Epi, class Sched, bool ALIGN_EPI = false, bool SP2 = false>
; __device__ __forceinline__ void gemm_phase(PG8_LAS unsigned char* lds, const Gemm g, const Sched& S, const Epi& E) {
;     ...
;         cur = nxt; cA = nA; cB = nB; ++ui;
;         if constexpr (ALIGN_EPI) { if (wr == 1) PG8_BAR; }
	v_pk_mul_f32 v[74:75], v[66:67], v[66:67]
	v_max_f32_e32 v67, v68, v68
	v_max_f32_e32 v70, 0, v70
	v_max_f32_e32 v71, 0, v71
	v_max_f32_e32 v66, v72, v72
	v_max_f32_e32 v68, 0, v67
	v_max_f32_e32 v67, v73, v73
	v_pk_mul_f32 v[70:71], v[70:71], v[70:71]
	v_max_f32_e32 v66, 0, v66
	v_max_f32_e32 v67, 0, v67
	v_max_f32_e32 v69, 0, v69
	v_pk_mul_f32 v[72:73], v[66:67], v[66:67]
	v_pk_mul_f32 v[76:77], v[68:69], v[68:69]
	v_cvt_pk_bf16_f32 v66, v70, v71
	v_lshl_add_u64 v[70:71], s[30:31], 0, v[144:145]
	v_cvt_pk_bf16_f32 v67, v72, v73
	v_cvt_pk_bf16_f32 v68, v74, v75
	v_cvt_pk_bf16_f32 v69, v76, v77
	v_lshl_add_u64 v[70:71], v[70:71], 0, v[138:139]
	v_max_f32_e32 v58, 0, v58
	v_max_f32_e32 v59, 0, v59
	global_store_dwordx4 v[70:71], v[66:69], off
	s_nop 1
	v_pk_mul_f32 v[66:67], v[58:59], v[58:59]
	v_max_f32_e32 v59, v60, v60
	v_max_f32_e32 v62, 0, v62
	v_max_f32_e32 v63, 0, v63
	v_max_f32_e32 v58, v64, v64
	v_max_f32_e32 v60, 0, v59
	v_max_f32_e32 v59, v65, v65
	v_pk_mul_f32 v[62:63], v[62:63], v[62:63]
	v_max_f32_e32 v58, 0, v58
	v_max_f32_e32 v59, 0, v59
	v_pk_mul_f32 v[64:65], v[58:59], v[58:59]
	v_cvt_pk_bf16_f32 v58, v62, v63
	v_add_co_u32_e32 v62, vcc, s43, v122
	v_max_f32_e32 v61, 0, v61
	s_nop 0
	v_addc_co_u32_e32 v63, vcc, 0, v123, vcc
	v_pk_mul_f32 v[68:69], v[60:61], v[60:61]
	v_cvt_pk_bf16_f32 v59, v64, v65
	v_add_co_u32_e32 v64, vcc, s50, v122
	v_cvt_pk_bf16_f32 v60, v66, v67
	v_cvt_pk_bf16_f32 v61, v68, v69
	v_addc_co_u32_e32 v65, vcc, 0, v123, vcc
	v_max_f32_e32 v50, 0, v50
	v_max_f32_e32 v51, 0, v51
	global_store_dwordx4 v[64:65], v[58:61], off offset:-4096
	s_nop 1
	v_pk_mul_f32 v[58:59], v[50:51], v[50:51]
	v_max_f32_e32 v51, v52, v52
	v_max_f32_e32 v54, 0, v54
	v_max_f32_e32 v55, 0, v55
	v_max_f32_e32 v50, v56, v56
	v_max_f32_e32 v52, 0, v51
	v_max_f32_e32 v51, v57, v57
	v_pk_mul_f32 v[54:55], v[54:55], v[54:55]
	v_max_f32_e32 v50, 0, v50
	v_max_f32_e32 v51, 0, v51
	v_pk_mul_f32 v[56:57], v[50:51], v[50:51]
	v_cvt_pk_bf16_f32 v50, v54, v55
	v_add_co_u32_e32 v54, vcc, s43, v114
	v_max_f32_e32 v53, 0, v53
	s_nop 0
	v_addc_co_u32_e32 v55, vcc, 0, v115, vcc
	v_pk_mul_f32 v[60:61], v[52:53], v[52:53]
	v_cvt_pk_bf16_f32 v51, v56, v57
	v_add_co_u32_e32 v56, vcc, s50, v114
	v_cvt_pk_bf16_f32 v52, v58, v59
	v_cvt_pk_bf16_f32 v53, v60, v61
	v_addc_co_u32_e32 v57, vcc, 0, v115, vcc
	v_max_f32_e32 v42, 0, v42
	v_max_f32_e32 v43, 0, v43
	global_store_dwordx4 v[56:57], v[50:53], off offset:-4096
	s_nop 1
	v_pk_mul_f32 v[50:51], v[42:43], v[42:43]
	v_max_f32_e32 v43, v44, v44
	v_max_f32_e32 v42, v48, v48
	v_max_f32_e32 v44, 0, v43
	v_max_f32_e32 v43, v49, v49
	v_max_f32_e32 v46, 0, v46
	v_max_f32_e32 v47, 0, v47
	v_max_f32_e32 v42, 0, v42
	v_max_f32_e32 v43, 0, v43
	v_max_f32_e32 v45, 0, v45
	v_pk_mul_f32 v[46:47], v[46:47], v[46:47]
	v_pk_mul_f32 v[48:49], v[42:43], v[42:43]
	v_pk_mul_f32 v[52:53], v[44:45], v[44:45]
	v_cvt_pk_bf16_f32 v42, v46, v47
	v_cvt_pk_bf16_f32 v43, v48, v49
	v_cvt_pk_bf16_f32 v44, v50, v51
	v_cvt_pk_bf16_f32 v45, v52, v53
	v_max_f32_e32 v34, 0, v34
	v_max_f32_e32 v35, 0, v35
	global_store_dwordx4 v[62:63], v[42:45], off offset:2048
	s_nop 1
	v_pk_mul_f32 v[42:43], v[34:35], v[34:35]
	v_max_f32_e32 v35, v36, v36
	v_max_f32_e32 v34, v40, v40
	v_max_f32_e32 v36, 0, v35
	v_max_f32_e32 v35, v41, v41
	v_max_f32_e32 v38, 0, v38
	v_max_f32_e32 v39, 0, v39
	v_max_f32_e32 v34, 0, v34
	v_max_f32_e32 v35, 0, v35
	v_max_f32_e32 v37, 0, v37
	v_pk_mul_f32 v[38:39], v[38:39], v[38:39]
	v_pk_mul_f32 v[40:41], v[34:35], v[34:35]
	v_pk_mul_f32 v[44:45], v[36:37], v[36:37]
	v_cvt_pk_bf16_f32 v34, v38, v39
	v_cvt_pk_bf16_f32 v35, v40, v41
	v_cvt_pk_bf16_f32 v36, v42, v43
	v_cvt_pk_bf16_f32 v37, v44, v45
	v_max_f32_e32 v26, 0, v26
	v_max_f32_e32 v27, 0, v27
	global_store_dwordx4 v[54:55], v[34:37], off offset:2048
	s_nop 1
	v_pk_mul_f32 v[34:35], v[26:27], v[26:27]
	v_max_f32_e32 v27, v28, v28
	v_max_f32_e32 v26, v32, v32
	v_max_f32_e32 v28, 0, v27
	v_max_f32_e32 v27, v33, v33
	v_max_f32_e32 v30, 0, v30
	v_max_f32_e32 v31, 0, v31
	v_max_f32_e32 v26, 0, v26
	v_max_f32_e32 v27, 0, v27
	v_max_f32_e32 v29, 0, v29
	v_pk_mul_f32 v[30:31], v[30:31], v[30:31]
	v_pk_mul_f32 v[32:33], v[26:27], v[26:27]
	v_pk_mul_f32 v[36:37], v[28:29], v[28:29]
	v_cvt_pk_bf16_f32 v26, v30, v31
	v_cvt_pk_bf16_f32 v27, v32, v33
	v_cvt_pk_bf16_f32 v28, v34, v35
	v_cvt_pk_bf16_f32 v29, v36, v37
	v_max_f32_e32 v18, 0, v18
	v_max_f32_e32 v19, 0, v19
	global_store_dwordx4 v[64:65], v[26:29], off
	s_nop 1
	v_pk_mul_f32 v[26:27], v[18:19], v[18:19]
	v_max_f32_e32 v19, v20, v20
	v_max_f32_e32 v18, v24, v24
	v_max_f32_e32 v20, 0, v19
	v_max_f32_e32 v19, v25, v25
	v_max_f32_e32 v22, 0, v22
	v_max_f32_e32 v23, 0, v23
	v_max_f32_e32 v18, 0, v18
	v_max_f32_e32 v19, 0, v19
	v_max_f32_e32 v21, 0, v21
	v_pk_mul_f32 v[22:23], v[22:23], v[22:23]
	v_pk_mul_f32 v[24:25], v[18:19], v[18:19]
	v_pk_mul_f32 v[28:29], v[20:21], v[20:21]
	v_cvt_pk_bf16_f32 v18, v22, v23
	v_cvt_pk_bf16_f32 v19, v24, v25
	v_cvt_pk_bf16_f32 v20, v26, v27
	v_cvt_pk_bf16_f32 v21, v28, v29
	v_max_f32_e32 v10, 0, v10
	v_max_f32_e32 v11, 0, v11
	global_store_dwordx4 v[56:57], v[18:21], off
	s_nop 1
	v_pk_mul_f32 v[18:19], v[10:11], v[10:11]
	v_max_f32_e32 v11, v12, v12
	v_max_f32_e32 v10, v16, v16
	v_max_f32_e32 v12, 0, v11
	v_max_f32_e32 v11, v17, v17
	v_max_f32_e32 v14, 0, v14
	v_max_f32_e32 v15, 0, v15
	v_max_f32_e32 v10, 0, v10
	v_max_f32_e32 v11, 0, v11
	v_max_f32_e32 v13, 0, v13
	v_pk_mul_f32 v[14:15], v[14:15], v[14:15]
	v_pk_mul_f32 v[16:17], v[10:11], v[10:11]
	v_pk_mul_f32 v[20:21], v[12:13], v[12:13]
	v_cvt_pk_bf16_f32 v10, v14, v15
	v_cvt_pk_bf16_f32 v11, v16, v17
	v_cvt_pk_bf16_f32 v12, v18, v19
	v_cvt_pk_bf16_f32 v13, v20, v21
	v_max_f32_e32 v2, 0, v2
	v_max_f32_e32 v3, 0, v3
	global_store_dwordx4 v[64:65], v[10:13], off offset:2048
	s_nop 1
	v_pk_mul_f32 v[10:11], v[2:3], v[2:3]
	v_max_f32_e32 v3, v4, v4
	v_max_f32_e32 v2, v8, v8
	v_max_f32_e32 v4, 0, v3
	v_max_f32_e32 v3, v9, v9
	v_max_f32_e32 v6, 0, v6
	v_max_f32_e32 v7, 0, v7
	v_max_f32_e32 v2, 0, v2
	v_max_f32_e32 v3, 0, v3
	v_max_f32_e32 v5, 0, v5
	v_pk_mul_f32 v[6:7], v[6:7], v[6:7]
	v_pk_mul_f32 v[8:9], v[2:3], v[2:3]
	v_pk_mul_f32 v[12:13], v[4:5], v[4:5]
	v_cvt_pk_bf16_f32 v2, v6, v7
	v_cvt_pk_bf16_f32 v3, v8, v9
	v_cvt_pk_bf16_f32 v4, v10, v11
	v_cvt_pk_bf16_f32 v5, v12, v13
	s_andn2_b64 vcc, exec, s[0:1]
	s_mov_b64 s[0:1], -1
	global_store_dwordx4 v[56:57], v[2:5], off offset:2048
	s_cbranch_vccnz .LBB0_1236
	s_andn2_b64 vcc, exec, s[6:7]
	s_cbranch_vccnz .LBB0_1235
	s_barrier
	s_branch .LBB0_1235
